# sample memory-attention unit: first K rows and cache touches of the 8 q rows issued at the top of the unit (setup had ~5 dependent load batches), stacked on v78
# baseline (speedup 1.0000x reference)
; __device__ __forceinline__ void memattn_unit(const Ctx& C, int r0, const float* kp0, const float* vp0, unsigned char* lds, int lane) {
;     const int w = C.wave, h = lane >> 4;
;     float* logits = (float*)lds;
;     const bf16_t* qmem = (const bf16_t*)(C.ws + WS_QMEM); const float* ssq = (const float*)(C.ws + ACC_SSQ);
;     {
;         unsigned q[8][8]; float rsq[8];
; #pragma unroll
;         for (int qi = 0; qi < 8; ++qi) { const u32x4 a = *(const u32x4*)(qmem + (size_t)(r0 + qi) * 1024 + lane * 16), bq = *(const u32x4*)(qmem + (size_t)(r0 + qi) * 1024 + lane * 16 + 8);
;             q[qi][0] = a.x; q[qi][1] = a.y; q[qi][2] = a.z; q[qi][3] = a.w; q[qi][4] = bq.x; q[qi][5] = bq.y; q[qi][6] = bq.z; q[qi][7] = bq.w;
;             rsq[qi] = (1.0f / sqrtf(ssq[(r0 + qi) * 4 + h] * (1.f / 256.f) + EPS)) * (0.0625f * 1.4426950408889634f); }
;         const float* kbase = kp0 + (size_t)(32 * w) * 1024 + lane * 16;
; #pragma unroll 1
;         for (int mb = 0; mb < 8; ++mb) {
;             f32x4 kr[4][4];
; #pragma unroll
;             for (int u = 0; u < 4; ++u)
; #pragma unroll
;                 for (int j = 0; j < 4; ++j) kr[u][j] = *(const f32x4*)(kbase + (size_t)(mb * 4 + u) * 1024 + 4 * j);
.LBB0_3144:
	s_lshl_b32 s12, s34, 3
	s_add_i32 s0, s12, 0x4000
	v_mbcnt_lo_u32_b32 v117, -1, 0
	v_mbcnt_hi_u32_b32 v117, -1, v117
	v_lshlrev_b32_e32 v236, 6, v117
	v_mov_b32_e32 v237, 0
	v_lshl_add_u64 v[236:237], s[22:23], 0, v[236:237]
	v_lshl_add_u64 v[238:239], v[236:237], 0, s[26:27]
	v_lshl_add_u64 v[240:241], v[236:237], 0, s[28:29]
	v_lshl_add_u64 v[242:243], v[236:237], 0, s[30:31]
	global_load_dwordx4 v[148:151], v[236:237], off
	global_load_dwordx4 v[152:155], v[236:237], off offset:16
	global_load_dwordx4 v[156:159], v[236:237], off offset:32
	global_load_dwordx4 v[160:163], v[236:237], off offset:48
	global_load_dwordx4 v[164:167], v[238:239], off
	global_load_dwordx4 v[168:171], v[238:239], off offset:16
	global_load_dwordx4 v[172:175], v[238:239], off offset:32
	global_load_dwordx4 v[176:179], v[238:239], off offset:48
	global_load_dwordx4 v[180:183], v[240:241], off
	global_load_dwordx4 v[184:187], v[240:241], off offset:16
	global_load_dwordx4 v[188:191], v[240:241], off offset:32
	global_load_dwordx4 v[192:195], v[240:241], off offset:48
	global_load_dwordx4 v[196:199], v[242:243], off
	global_load_dwordx4 v[200:203], v[242:243], off offset:16
	global_load_dwordx4 v[204:207], v[242:243], off offset:32
	global_load_dwordx4 v[208:211], v[242:243], off offset:48
	v_lshlrev_b32_e32 v244, 5, v117
	v_mov_b32_e32 v245, 0
	v_lshl_add_u64 v[244:245], s[18:19], 0, v[244:245]
	s_lshl_b32 s98, s0, 11
	s_mov_b32 s99, 0
	v_lshl_add_u64 v[244:245], v[244:245], 0, s[98:99]
	global_load_dwordx4 v[212:215], v[244:245], off
	global_load_dwordx4 v[216:219], v[244:245], off offset:16
	global_load_dwordx4 v[220:223], v[244:245], off offset:2048
	global_load_dwordx4 v[224:227], v[244:245], off offset:2064
	v_lshl_add_u64 v[244:245], v[244:245], 0, s[26:27]
	global_load_dwordx4 v[212:215], v[244:245], off
	global_load_dwordx4 v[216:219], v[244:245], off offset:16
	global_load_dwordx4 v[220:223], v[244:245], off offset:2048
	global_load_dwordx4 v[224:227], v[244:245], off offset:2064
	v_lshl_add_u64 v[244:245], v[244:245], 0, s[26:27]
	global_load_dwordx4 v[212:215], v[244:245], off
	global_load_dwordx4 v[216:219], v[244:245], off offset:16
	global_load_dwordx4 v[220:223], v[244:245], off offset:2048
	global_load_dwordx4 v[224:227], v[244:245], off offset:2064
	v_lshl_add_u64 v[244:245], v[244:245], 0, s[26:27]
	global_load_dwordx4 v[212:215], v[244:245], off
	global_load_dwordx4 v[216:219], v[244:245], off offset:16
	global_load_dwordx4 v[220:223], v[244:245], off offset:2048
	global_load_dwordx4 v[224:227], v[244:245], off offset:2064
	s_add_i32 s4, s12, 0x4001
	v_ashrrev_i32_e32 v66, 4, v117
	v_lshl_add_u32 v0, s0, 2, v66
	v_ashrrev_i32_e32 v1, 31, v0
	v_lshl_add_u64 v[0:1], v[0:1], 2, s[8:9]
	global_load_dword v28, v[0:1], off
	v_lshl_add_u32 v0, s4, 2, v66
	v_ashrrev_i32_e32 v1, 31, v0
	v_lshl_add_u64 v[0:1], v[0:1], 2, s[8:9]
	s_add_i32 s40, s12, 0x4002
	global_load_dword v29, v[0:1], off
	v_lshl_add_u32 v0, s40, 2, v66
	v_ashrrev_i32_e32 v1, 31, v0
	v_lshl_add_u64 v[0:1], v[0:1], 2, s[8:9]
	global_load_dword v30, v[0:1], off
	v_lshlrev_b32_e32 v64, 4, v117
	v_ashrrev_i32_e32 v65, 31, v64
	s_ashr_i32 s5, s4, 31
	s_waitcnt vmcnt(18)
	v_lshl_add_u64 v[52:53], v[64:65], 1, s[18:19]
	s_lshl_b64 s[4:5], s[4:5], 11
	s_waitcnt vmcnt(10)
	v_lshl_add_u64 v[12:13], v[52:53], 0, s[4:5]
	s_add_i32 s4, s12, 0x4003
	s_add_i32 s38, s12, 0x4004
	s_ashr_i32 s1, s0, 31
	s_ashr_i32 s5, s4, 31
	v_lshl_add_u32 v4, s4, 2, v66
	s_waitcnt vmcnt(3)
	v_lshl_add_u32 v6, s38, 2, v66
	s_lshl_b64 s[36:37], s[0:1], 11
	s_lshl_b64 s[0:1], s[4:5], 11
	v_ashrrev_i32_e32 v5, 31, v4
	v_ashrrev_i32_e32 v7, 31, v6
	v_lshl_add_u64 v[8:9], v[52:53], 0, s[36:37]
	v_lshl_add_u64 v[20:21], v[52:53], 0, s[0:1]
	global_load_dwordx4 v[0:3], v[12:13], off offset:16
	v_lshl_add_u64 v[24:25], v[4:5], 2, s[8:9]
	v_lshl_add_u64 v[26:27], v[6:7], 2, s[8:9]
	global_load_dwordx4 v[4:7], v[8:9], off
	s_nop 0
	global_load_dwordx4 v[8:11], v[8:9], off offset:16
	s_nop 0
	global_load_dwordx4 v[12:15], v[12:13], off
	s_nop 0
	global_load_dwordx4 v[16:19], v[20:21], off
	s_nop 0
	global_load_dwordx4 v[20:23], v[20:21], off offset:16
	s_nop 0
	global_load_dword v32, v[24:25], off
	s_ashr_i32 s41, s40, 31
	s_ashr_i32 s39, s38, 31
	v_lshl_add_u32 v126, v66, 10, s3
	v_lshl_add_u64 v[112:113], v[64:65], 2, s[22:23]
	s_waitcnt vmcnt(9)
	v_fmamk_f32 v24, v28, 0x3b800000, v114
	v_cmp_gt_f32_e32 vcc, s47, v24
	s_waitcnt vmcnt(8)
	v_fmamk_f32 v25, v29, 0x3b800000, v114
	v_mul_f32_e32 v29, 0x4f800000, v24
	v_cndmask_b32_e32 v24, v24, v29, vcc
	v_cmp_gt_f32_e64 s[0:1], s47, v25
	s_waitcnt vmcnt(7)
	v_fmamk_f32 v28, v30, 0x3b800000, v114
	v_mul_f32_e32 v30, 0x4f800000, v25
	v_cndmask_b32_e64 v25, v25, v30, s[0:1]
	v_sqrt_f32_e32 v29, v24
	v_sqrt_f32_e32 v30, v25
	v_mul_f32_e32 v31, 0x4f800000, v28
	v_cmp_gt_f32_e64 s[4:5], s47, v28
	v_add_u32_e32 v33, -1, v29
	v_add_u32_e32 v35, -1, v30
	v_fma_f32 v37, -v33, v29, v24
	v_add_u32_e32 v34, 1, v29
	v_fma_f32 v39, -v35, v30, v25
	v_cmp_ge_f32_e64 s[6:7], 0, v37
	v_add_u32_e32 v36, 1, v30
	v_fma_f32 v38, -v34, v29, v24
	v_cndmask_b32_e64 v29, v29, v33, s[6:7]
	v_cmp_ge_f32_e64 s[6:7], 0, v39
	v_fma_f32 v40, -v36, v30, v25
	v_cndmask_b32_e64 v28, v28, v31, s[4:5]
	v_cndmask_b32_e64 v30, v30, v35, s[6:7]
	v_cmp_lt_f32_e64 s[6:7], 0, v38
	v_sqrt_f32_e32 v31, v28
	s_waitcnt vmcnt(0)
; __device__ __forceinline__ void memattn_unit(const Ctx& C, int r0, const float* kp0, const float* vp0, unsigned char* lds, int lane) {
;     ...
;         unsigned q[8][8]; float rsq[8];
; #pragma unroll
;         for (int qi = 0; qi < 8; ++qi) { const u32x4 a = *(const u32x4*)(qmem + (size_t)(r0 + qi) * 1024 + lane * 16), bq = *(const u32x4*)(qmem + (size_t)(r0 + qi) * 1024 + lane * 16 + 8);
;             q[qi][0] = a.x; q[qi][1] = a.y; q[qi][2] = a.z; q[qi][3] = a.w; q[qi][4] = bq.x; q[qi][5] = bq.y; q[qi][6] = bq.z; q[qi][7] = bq.w;
;             rsq[qi] = (1.0f / sqrtf(ssq[(r0 + qi) * 4 + h] * (1.f / 256.f) + EPS)) * (0.0625f * 1.4426950408889634f); }
	v_fmamk_f32 v32, v32, 0x3b800000, v114
	v_cndmask_b32_e64 v29, v29, v34, s[6:7]
	v_cmp_lt_f32_e64 s[6:7], 0, v40
	v_mul_f32_e32 v33, 0x37800000, v29
	v_cndmask_b32_e32 v29, v29, v33, vcc
	v_cndmask_b32_e64 v30, v30, v36, s[6:7]
	v_mul_f32_e32 v34, 0x37800000, v30
	v_cmp_class_f32_e32 vcc, v24, v115
	v_cndmask_b32_e64 v30, v30, v34, s[0:1]
	s_nop 0
	v_cndmask_b32_e32 v24, v29, v24, vcc
	v_cmp_class_f32_e32 vcc, v25, v115
	v_div_scale_f32 v29, s[0:1], v24, v24, 1.0
	s_nop 0
	v_cndmask_b32_e32 v25, v30, v25, vcc
	v_div_scale_f32 v33, s[0:1], v25, v25, 1.0
	v_rcp_f32_e32 v35, v33
	v_div_scale_f32 v36, s[0:1], 1.0, v25, 1.0
	v_rcp_f32_e32 v34, v29
	v_fma_f32 v38, -v33, v35, 1.0
	v_fmac_f32_e32 v35, v38, v35
	v_mul_f32_e32 v38, v36, v35
	v_fma_f32 v40, -v33, v38, v36
	v_fmac_f32_e32 v38, v40, v35
	global_load_dword v40, v[26:27], off
	v_fma_f32 v37, -v29, v34, 1.0
	v_div_scale_f32 v30, vcc, 1.0, v24, 1.0
	v_fmac_f32_e32 v34, v37, v34
	v_mul_f32_e32 v37, v30, v34
	v_fma_f32 v39, -v29, v37, v30
	v_fmac_f32_e32 v37, v39, v34
	v_fma_f32 v29, -v29, v37, v30
	v_fma_f32 v30, -v33, v38, v36
	v_div_fmas_f32 v29, v29, v34, v37
	s_mov_b64 vcc, s[0:1]
	v_div_fixup_f32 v24, v29, v24, 1.0
	v_div_fmas_f32 v29, v30, v35, v38
	v_mul_f32_e32 v118, 0x3db8aa3b, v24
	v_div_fixup_f32 v24, v29, v25, 1.0
	v_mul_f32_e32 v119, 0x3db8aa3b, v24
	v_add_u32_e32 v24, -1, v31
	v_fma_f32 v25, -v24, v31, v28
	v_cmp_ge_f32_e32 vcc, 0, v25
	v_add_u32_e32 v25, 1, v31
	v_fma_f32 v26, -v25, v31, v28
	v_cndmask_b32_e32 v24, v31, v24, vcc
	v_cmp_lt_f32_e32 vcc, 0, v26
	s_lshl_b64 s[0:1], s[40:41], 11
	s_waitcnt vmcnt(0)
	v_fmamk_f32 v40, v40, 0x3b800000, v114
	v_cndmask_b32_e32 v24, v24, v25, vcc
	v_mul_f32_e32 v25, 0x37800000, v24
	v_cndmask_b32_e64 v24, v24, v25, s[4:5]
	v_cmp_class_f32_e32 vcc, v28, v115
	s_nop 1
	v_cndmask_b32_e32 v41, v24, v28, vcc
	v_div_scale_f32 v42, s[4:5], v41, v41, 1.0
	v_rcp_f32_e32 v43, v42
	s_add_i32 s4, s12, 0x4005
	v_lshl_add_u64 v[28:29], v[52:53], 0, s[0:1]
	v_cmp_gt_f32_e64 s[0:1], s47, v32
	v_fma_f32 v33, -v42, v43, 1.0
	v_fmac_f32_e32 v43, v33, v43
	v_mul_f32_e32 v33, 0x4f800000, v32
	s_ashr_i32 s5, s4, 31
	v_cndmask_b32_e64 v46, v32, v33, s[0:1]
	s_lshl_b64 s[6:7], s[4:5], 11
	v_lshl_add_u32 v32, s4, 2, v66
	v_lshl_add_u64 v[36:37], v[52:53], 0, s[6:7]
	v_ashrrev_i32_e32 v33, 31, v32
	global_load_dwordx4 v[24:27], v[28:29], off
	s_nop 0
	global_load_dwordx4 v[28:31], v[28:29], off offset:16
	v_lshl_add_u64 v[38:39], v[32:33], 2, s[8:9]
	global_load_dwordx4 v[32:35], v[36:37], off offset:16
	global_load_dword v54, v[38:39], off
	v_sqrt_f32_e32 v47, v46
	v_div_scale_f32 v44, vcc, 1.0, v41, 1.0
	v_mul_f32_e32 v45, v44, v43
	v_fma_f32 v38, -v42, v45, v44
	v_fmac_f32_e32 v45, v38, v43
	v_add_u32_e32 v39, -1, v47
	v_fma_f32 v38, -v42, v45, v44
	v_fma_f32 v42, -v39, v47, v46
	v_cmp_ge_f32_e64 s[4:5], 0, v42
	v_add_u32_e32 v42, 1, v47
	v_fma_f32 v44, -v42, v47, v46
	v_cndmask_b32_e64 v39, v47, v39, s[4:5]
	v_cmp_lt_f32_e64 s[4:5], 0, v44
	v_div_fmas_f32 v38, v38, v43, v45
	v_div_fixup_f32 v38, v38, v41, 1.0
	v_cndmask_b32_e64 v39, v39, v42, s[4:5]
	v_mul_f32_e32 v42, 0x37800000, v39
	v_cndmask_b32_e64 v39, v39, v42, s[0:1]
	v_cmp_class_f32_e64 s[0:1], v46, v115
	v_mul_f32_e32 v120, 0x3db8aa3b, v38
	s_add_i32 s6, s12, 0x4006
	v_cndmask_b32_e64 v39, v39, v46, s[0:1]
	v_div_scale_f32 v42, s[0:1], v39, v39, 1.0
	v_rcp_f32_e32 v44, v42
	s_lshl_b64 s[4:5], s[38:39], 11
	v_lshl_add_u64 v[48:49], v[52:53], 0, s[4:5]
	s_ashr_i32 s7, s6, 31
	v_fma_f32 v38, -v42, v44, 1.0
	v_fmac_f32_e32 v44, v38, v44
	v_div_scale_f32 v38, vcc, 1.0, v39, 1.0
	v_mul_f32_e32 v41, v38, v44
	v_fma_f32 v43, -v42, v41, v38
	v_fmac_f32_e32 v41, v43, v44
	v_fma_f32 v38, -v42, v41, v38
	v_div_fmas_f32 v38, v38, v44, v41
	v_div_fixup_f32 v41, v38, v39, 1.0
	v_lshl_add_u32 v38, s6, 2, v66
	v_ashrrev_i32_e32 v39, 31, v38
	v_mul_f32_e32 v42, 0x4f800000, v40
	v_cmp_gt_f32_e32 vcc, s47, v40
	v_lshl_add_u64 v[38:39], v[38:39], 2, s[8:9]
	global_load_dword v67, v[38:39], off
	s_nop 0
	global_load_dwordx4 v[36:39], v[36:37], off
	v_cndmask_b32_e32 v40, v40, v42, vcc
	v_sqrt_f32_e32 v42, v40
	v_mul_f32_e32 v121, 0x3db8aa3b, v41
	v_add_u32_e32 v41, -1, v42
	v_fma_f32 v43, -v41, v42, v40
	v_cmp_ge_f32_e64 s[0:1], 0, v43
	v_add_u32_e32 v43, 1, v42
	s_waitcnt vmcnt(2)
	v_fmamk_f32 v54, v54, 0x3b800000, v114
	v_cndmask_b32_e64 v41, v42, v41, s[0:1]
	v_fma_f32 v42, -v43, v42, v40
	v_cmp_lt_f32_e64 s[0:1], 0, v42
	v_mul_f32_e32 v62, 0x4f800000, v54
	s_waitcnt vmcnt(1)
; __device__ __forceinline__ void memattn_unit(const Ctx& C, int r0, const float* kp0, const float* vp0, unsigned char* lds, int lane) {
;     ...
;         unsigned q[8][8]; float rsq[8];
; #pragma unroll
;         for (int qi = 0; qi < 8; ++qi) { const u32x4 a = *(const u32x4*)(qmem + (size_t)(r0 + qi) * 1024 + lane * 16), bq = *(const u32x4*)(qmem + (size_t)(r0 + qi) * 1024 + lane * 16 + 8);
;             q[qi][0] = a.x; q[qi][1] = a.y; q[qi][2] = a.z; q[qi][3] = a.w; q[qi][4] = bq.x; q[qi][5] = bq.y; q[qi][6] = bq.z; q[qi][7] = bq.w;
;             rsq[qi] = (1.0f / sqrtf(ssq[(r0 + qi) * 4 + h] * (1.f / 256.f) + EPS)) * (0.0625f * 1.4426950408889634f); }
;         const float* kbase = kp0 + (size_t)(32 * w) * 1024 + lane * 16;
; #pragma unroll 1
;         for (int mb = 0; mb < 8; ++mb) {
;             f32x4 kr[4][4];
; #pragma unroll
;             for (int u = 0; u < 4; ++u)
; #pragma unroll
;                 for (int j = 0; j < 4; ++j) kr[u][j] = *(const f32x4*)(kbase + (size_t)(mb * 4 + u) * 1024 + 4 * j);
	v_fmamk_f32 v67, v67, 0x3b800000, v114
	v_cndmask_b32_e64 v41, v41, v43, s[0:1]
	v_mul_f32_e32 v42, 0x37800000, v41
	v_cndmask_b32_e32 v41, v41, v42, vcc
	v_cmp_class_f32_e32 vcc, v40, v115
	v_mul_f32_e32 v74, 0x4f800000, v67
	s_nop 0
	v_cndmask_b32_e32 v55, v41, v40, vcc
	v_div_scale_f32 v56, s[0:1], v55, v55, 1.0
	s_add_i32 s0, s12, 0x4007
	s_ashr_i32 s1, s0, 31
	s_lshl_b64 s[38:39], s[0:1], 11
	v_lshl_add_u32 v40, s0, 2, v66
	v_lshl_add_u64 v[60:61], v[52:53], 0, s[38:39]
	v_ashrrev_i32_e32 v41, 31, v40
	v_lshl_add_u64 v[44:45], v[40:41], 2, s[8:9]
	global_load_dwordx4 v[40:43], v[60:61], off offset:16
	global_load_dword v68, v[44:45], off
	v_rcp_f32_e32 v57, v56
	v_cmp_gt_f32_e64 s[0:1], s47, v54
	global_load_dwordx4 v[44:47], v[48:49], off
	s_nop 0
	global_load_dwordx4 v[48:51], v[48:49], off offset:16
	v_cndmask_b32_e64 v54, v54, v62, s[0:1]
	v_fma_f32 v58, -v56, v57, 1.0
	v_fmac_f32_e32 v57, v58, v57
	v_div_scale_f32 v58, vcc, 1.0, v55, 1.0
	v_sqrt_f32_e32 v62, v54
	v_mul_f32_e32 v59, v58, v57
	v_fma_f32 v63, -v56, v59, v58
	v_fmac_f32_e32 v59, v63, v57
	v_fma_f32 v56, -v56, v59, v58
	v_add_u32_e32 v58, -1, v62
	v_fma_f32 v63, -v58, v62, v54
	v_cmp_ge_f32_e64 s[4:5], 0, v63
	v_add_u32_e32 v63, 1, v62
	s_waitcnt vmcnt(2)
	v_fmamk_f32 v68, v68, 0x3b800000, v114
	v_cndmask_b32_e64 v58, v62, v58, s[4:5]
	v_fma_f32 v62, -v63, v62, v54
	v_cmp_lt_f32_e64 s[4:5], 0, v62
	s_nop 1
	v_cndmask_b32_e64 v58, v58, v63, s[4:5]
	v_mul_f32_e32 v62, 0x37800000, v58
	v_cndmask_b32_e64 v58, v58, v62, s[0:1]
	v_cmp_class_f32_e64 s[0:1], v54, v115
	s_nop 1
	v_cndmask_b32_e64 v69, v58, v54, s[0:1]
	v_div_scale_f32 v70, s[0:1], v69, v69, 1.0
	v_rcp_f32_e32 v71, v70
	v_div_fmas_f32 v54, v56, v57, v59
	v_div_fixup_f32 v54, v54, v55, 1.0
	s_lshl_b64 s[0:1], s[6:7], 11
	v_mul_f32_e32 v122, 0x3db8aa3b, v54
	v_fma_f32 v54, -v70, v71, 1.0
	v_lshl_add_u64 v[56:57], v[52:53], 0, s[0:1]
	v_fmac_f32_e32 v71, v54, v71
	global_load_dwordx4 v[52:55], v[56:57], off
	s_nop 0
	global_load_dwordx4 v[56:59], v[56:57], off offset:16
	s_nop 0
	global_load_dwordx4 v[60:63], v[60:61], off
	v_cmp_gt_f32_e64 s[0:1], s47, v67
	v_div_scale_f32 v72, vcc, 1.0, v69, 1.0
	s_nop 0
	v_cndmask_b32_e64 v67, v67, v74, s[0:1]
	v_sqrt_f32_e32 v74, v67
	v_mul_f32_e32 v73, v72, v71
	v_fma_f32 v75, -v70, v73, v72
	v_fmac_f32_e32 v73, v75, v71
	v_fma_f32 v70, -v70, v73, v72
	v_add_u32_e32 v72, -1, v74
	v_fma_f32 v75, -v72, v74, v67
	v_cmp_ge_f32_e64 s[4:5], 0, v75
	v_add_u32_e32 v75, 1, v74
	v_div_fmas_f32 v70, v70, v71, v73
	v_cndmask_b32_e64 v72, v74, v72, s[4:5]
	v_fma_f32 v74, -v75, v74, v67
	v_cmp_lt_f32_e64 s[4:5], 0, v74
	v_div_fixup_f32 v69, v70, v69, 1.0
	v_mul_f32_e32 v71, 0x4f800000, v68
	v_cndmask_b32_e64 v72, v72, v75, s[4:5]
	v_mul_f32_e32 v74, 0x37800000, v72
	v_cndmask_b32_e64 v72, v72, v74, s[0:1]
	v_cmp_class_f32_e64 s[0:1], v67, v115
	v_mul_f32_e32 v123, 0x3db8aa3b, v69
	s_nop 0
	v_cndmask_b32_e64 v67, v72, v67, s[0:1]
	v_div_scale_f32 v72, s[0:1], v67, v67, 1.0
	v_rcp_f32_e32 v74, v72
	v_cmp_gt_f32_e64 s[0:1], s47, v68
	v_fma_f32 v69, -v72, v74, 1.0
	s_nop 0
	v_cndmask_b32_e64 v68, v68, v71, s[0:1]
	v_fmac_f32_e32 v74, v69, v74
	v_div_scale_f32 v69, vcc, 1.0, v67, 1.0
	v_sqrt_f32_e32 v71, v68
	v_mul_f32_e32 v70, v69, v74
	v_fma_f32 v73, -v72, v70, v69
	v_fmac_f32_e32 v70, v73, v74
	v_fma_f32 v69, -v72, v70, v69
	v_add_u32_e32 v72, -1, v71
	v_fma_f32 v73, -v72, v71, v68
	v_cmp_ge_f32_e64 s[4:5], 0, v73
	v_add_u32_e32 v73, 1, v71
	v_div_fmas_f32 v69, v69, v74, v70
	v_cndmask_b32_e64 v72, v71, v72, s[4:5]
	v_fma_f32 v71, -v73, v71, v68
	v_cmp_lt_f32_e64 s[4:5], 0, v71
	v_div_fixup_f32 v67, v69, v67, 1.0
	v_mul_f32_e32 v124, 0x3db8aa3b, v67
	v_cndmask_b32_e64 v71, v72, v73, s[4:5]
	v_mul_f32_e32 v72, 0x37800000, v71
	v_cndmask_b32_e64 v71, v71, v72, s[0:1]
	v_cmp_class_f32_e64 s[0:1], v68, v115
	s_mov_b64 s[4:5], 0
	s_nop 0
	v_cndmask_b32_e64 v68, v71, v68, s[0:1]
	v_div_scale_f32 v71, s[0:1], v68, v68, 1.0
	v_rcp_f32_e32 v72, v71
	s_nop 0
	v_fma_f32 v67, -v71, v72, 1.0
	v_fmac_f32_e32 v72, v67, v72
	v_div_scale_f32 v67, vcc, 1.0, v68, 1.0
	v_mul_f32_e32 v69, v67, v72
	v_fma_f32 v70, -v71, v69, v67
	v_fmac_f32_e32 v69, v70, v72
	v_fma_f32 v67, -v71, v69, v67
	v_div_fmas_f32 v67, v67, v72, v69
	v_div_fixup_f32 v67, v67, v68, 1.0
	v_mul_f32_e32 v125, 0x3db8aa3b, v67
	v_and_b32_e32 v67, 15, v117
	v_cmp_eq_u32_e32 vcc, 0, v67
	s_waitcnt vmcnt(0)
